# P1 K_NONE / K_SCALE tile epilogues: stores issued one group behind their ds_bpermutes (counted lgkmcnt) instead of waiting for each group
# speedup vs baseline: 1.0020x; 1.0020x over previous
.LBB0_147:
	s_andn2_b64 vcc, exec, s[76:77]
	s_cbranch_vccnz .LBB0_149
	v_lshl_add_u32 v135, v150, 4, v3
	v_and_b32_e32 v134, 15, v3
	v_sub_u32_e32 v134, v5, v134
	v_ashrrev_i32_e32 v136, 2, v135
	v_add_u32_e32 v134, v136, v134
	v_and_b32_e32 v137, 3, v3
	v_ashrrev_i32_e32 v136, 1, v135
	v_and_b32_e32 v136, -8, v136
	v_lshlrev_b32_e32 v138, 3, v137
	v_add_u32_e32 v138, v4, v138
	v_sub_u32_e32 v136, v138, v136
	v_lshlrev_b32_e32 v137, 6, v137
	v_and_or_b32 v151, v135, -4, v137
	v_readlane_b32 s0, v254, 41
	v_readlane_b32 s1, v254, 42
	v_ashrrev_i32_e32 v137, 31, v136
	v_ashrrev_i32_e32 v135, 31, v134
	v_lshlrev_b64 v[134:135], 9, v[134:135]
	v_lshl_add_u64 v[136:137], v[136:137], 1, s[0:1]
	v_lshl_add_u64 v[136:137], v[136:137], 0, v[134:135]
.Lt_none9:
	v_mov_b64_e32 v[138:139], v[136:137]
	v_cvt_pk_bf16_f32 v160, v102, v103
	v_cvt_pk_bf16_f32 v161, v104, v105
	v_cvt_pk_bf16_f32 v162, v70, v71
	v_cvt_pk_bf16_f32 v163, v72, v73
	ds_bpermute_b32 v164, v151, v160
	ds_bpermute_b32 v165, v151, v161
	ds_bpermute_b32 v166, v151, v162
	ds_bpermute_b32 v167, v151, v163
	v_cvt_pk_bf16_f32 v176, v130, v131
	v_cvt_pk_bf16_f32 v177, v132, v133
	v_cvt_pk_bf16_f32 v178, v98, v99
	v_cvt_pk_bf16_f32 v179, v100, v101
	ds_bpermute_b32 v180, v151, v176
	ds_bpermute_b32 v181, v151, v177
	ds_bpermute_b32 v182, v151, v178
	ds_bpermute_b32 v183, v151, v179
	s_waitcnt lgkmcnt(4)
	global_store_dwordx4 v[138:139], v[164:167], off nt
	s_mov_b64 s[2:3], 0x2000
	v_lshl_add_u64 v[140:141], v[136:137], 0, s[2:3]
	v_cvt_pk_bf16_f32 v160, v114, v115
	v_cvt_pk_bf16_f32 v161, v116, v117
	v_cvt_pk_bf16_f32 v162, v82, v83
	v_cvt_pk_bf16_f32 v163, v84, v85
	ds_bpermute_b32 v164, v151, v160
	ds_bpermute_b32 v165, v151, v161
	ds_bpermute_b32 v166, v151, v162
	ds_bpermute_b32 v167, v151, v163
	s_waitcnt lgkmcnt(4)
	global_store_dwordx4 v[138:139], v[180:183], off offset:256 nt
	v_cvt_pk_bf16_f32 v176, v126, v127
	v_cvt_pk_bf16_f32 v177, v128, v129
	v_cvt_pk_bf16_f32 v178, v94, v95
	v_cvt_pk_bf16_f32 v179, v96, v97
	ds_bpermute_b32 v180, v151, v176
	ds_bpermute_b32 v181, v151, v177
	ds_bpermute_b32 v182, v151, v178
	ds_bpermute_b32 v183, v151, v179
	s_waitcnt lgkmcnt(4)
	global_store_dwordx4 v[140:141], v[164:167], off nt
	s_mov_b64 s[2:3], 0x4000
	v_lshl_add_u64 v[138:139], v[136:137], 0, s[2:3]
	v_cvt_pk_bf16_f32 v160, v110, v111
	v_cvt_pk_bf16_f32 v161, v112, v113
	v_cvt_pk_bf16_f32 v162, v78, v79
	v_cvt_pk_bf16_f32 v163, v80, v81
	ds_bpermute_b32 v164, v151, v160
	ds_bpermute_b32 v165, v151, v161
	ds_bpermute_b32 v166, v151, v162
	ds_bpermute_b32 v167, v151, v163
	s_waitcnt lgkmcnt(4)
	global_store_dwordx4 v[140:141], v[180:183], off offset:256 nt
	v_cvt_pk_bf16_f32 v176, v122, v123
	v_cvt_pk_bf16_f32 v177, v124, v125
	v_cvt_pk_bf16_f32 v178, v90, v91
	v_cvt_pk_bf16_f32 v179, v92, v93
	ds_bpermute_b32 v180, v151, v176
	ds_bpermute_b32 v181, v151, v177
	ds_bpermute_b32 v182, v151, v178
	ds_bpermute_b32 v183, v151, v179
	s_waitcnt lgkmcnt(4)
	global_store_dwordx4 v[138:139], v[164:167], off nt
	s_mov_b64 s[2:3], 0x6000
	v_lshl_add_u64 v[140:141], v[136:137], 0, s[2:3]
	v_cvt_pk_bf16_f32 v160, v106, v107
	v_cvt_pk_bf16_f32 v161, v108, v109
	v_cvt_pk_bf16_f32 v162, v74, v75
	v_cvt_pk_bf16_f32 v163, v76, v77
	ds_bpermute_b32 v164, v151, v160
	ds_bpermute_b32 v165, v151, v161
	ds_bpermute_b32 v166, v151, v162
	ds_bpermute_b32 v167, v151, v163
	s_waitcnt lgkmcnt(4)
	global_store_dwordx4 v[138:139], v[180:183], off offset:256 nt
	v_cvt_pk_bf16_f32 v176, v118, v119
	v_cvt_pk_bf16_f32 v177, v120, v121
	v_cvt_pk_bf16_f32 v178, v86, v87
	v_cvt_pk_bf16_f32 v179, v88, v89
	ds_bpermute_b32 v180, v151, v176
	ds_bpermute_b32 v181, v151, v177
	ds_bpermute_b32 v182, v151, v178
	ds_bpermute_b32 v183, v151, v179
	s_waitcnt lgkmcnt(4)
	global_store_dwordx4 v[140:141], v[164:167], off nt
	s_mov_b64 s[2:3], 0x10000
	v_lshl_add_u64 v[138:139], v[136:137], 0, s[2:3]
	v_cvt_pk_bf16_f32 v160, v38, v39
	v_cvt_pk_bf16_f32 v161, v40, v41
	v_cvt_pk_bf16_f32 v162, v6, v7
	v_cvt_pk_bf16_f32 v163, v8, v9
	ds_bpermute_b32 v164, v151, v160
	ds_bpermute_b32 v165, v151, v161
	ds_bpermute_b32 v166, v151, v162
	ds_bpermute_b32 v167, v151, v163
	s_waitcnt lgkmcnt(4)
	global_store_dwordx4 v[140:141], v[180:183], off offset:256 nt
	v_cvt_pk_bf16_f32 v176, v62, v63
	v_cvt_pk_bf16_f32 v177, v64, v65
	v_cvt_pk_bf16_f32 v178, v30, v31
	v_cvt_pk_bf16_f32 v179, v32, v33
	ds_bpermute_b32 v180, v151, v176
	ds_bpermute_b32 v181, v151, v177
	ds_bpermute_b32 v182, v151, v178
	ds_bpermute_b32 v183, v151, v179
	s_waitcnt lgkmcnt(4)
	global_store_dwordx4 v[138:139], v[164:167], off nt
	s_mov_b64 s[2:3], 0x12000
	v_lshl_add_u64 v[140:141], v[136:137], 0, s[2:3]
	v_cvt_pk_bf16_f32 v160, v50, v51
	v_cvt_pk_bf16_f32 v161, v52, v53
	v_cvt_pk_bf16_f32 v162, v18, v19
	v_cvt_pk_bf16_f32 v163, v20, v21
	ds_bpermute_b32 v164, v151, v160
	ds_bpermute_b32 v165, v151, v161
	ds_bpermute_b32 v166, v151, v162
	ds_bpermute_b32 v167, v151, v163
	s_waitcnt lgkmcnt(4)
	global_store_dwordx4 v[138:139], v[180:183], off offset:256 nt
	v_cvt_pk_bf16_f32 v176, v66, v67
	v_cvt_pk_bf16_f32 v177, v68, v69
	v_cvt_pk_bf16_f32 v178, v34, v35
	v_cvt_pk_bf16_f32 v179, v36, v37
	ds_bpermute_b32 v180, v151, v176
	ds_bpermute_b32 v181, v151, v177
	ds_bpermute_b32 v182, v151, v178
	ds_bpermute_b32 v183, v151, v179
	s_waitcnt lgkmcnt(4)
	global_store_dwordx4 v[140:141], v[164:167], off nt
	s_mov_b64 s[2:3], 0x14000
	v_lshl_add_u64 v[138:139], v[136:137], 0, s[2:3]
	v_cvt_pk_bf16_f32 v160, v46, v47
	v_cvt_pk_bf16_f32 v161, v48, v49
	v_cvt_pk_bf16_f32 v162, v14, v15
	v_cvt_pk_bf16_f32 v163, v16, v17
	ds_bpermute_b32 v164, v151, v160
	ds_bpermute_b32 v165, v151, v161
	ds_bpermute_b32 v166, v151, v162
	ds_bpermute_b32 v167, v151, v163
	s_waitcnt lgkmcnt(4)
	global_store_dwordx4 v[140:141], v[180:183], off offset:256 nt
	v_cvt_pk_bf16_f32 v176, v58, v59
	v_cvt_pk_bf16_f32 v177, v60, v61
	v_cvt_pk_bf16_f32 v178, v26, v27
	v_cvt_pk_bf16_f32 v179, v28, v29
	ds_bpermute_b32 v180, v151, v176
	ds_bpermute_b32 v181, v151, v177
	ds_bpermute_b32 v182, v151, v178
	ds_bpermute_b32 v183, v151, v179
	s_waitcnt lgkmcnt(4)
	global_store_dwordx4 v[138:139], v[164:167], off nt
	s_mov_b64 s[2:3], 0x16000
	v_lshl_add_u64 v[140:141], v[136:137], 0, s[2:3]
	v_cvt_pk_bf16_f32 v160, v42, v43
	v_cvt_pk_bf16_f32 v161, v44, v45
	v_cvt_pk_bf16_f32 v162, v10, v11
	v_cvt_pk_bf16_f32 v163, v12, v13
	ds_bpermute_b32 v164, v151, v160
	ds_bpermute_b32 v165, v151, v161
	ds_bpermute_b32 v166, v151, v162
	ds_bpermute_b32 v167, v151, v163
	s_waitcnt lgkmcnt(4)
	global_store_dwordx4 v[138:139], v[180:183], off offset:256 nt
	v_cvt_pk_bf16_f32 v176, v54, v55
	v_cvt_pk_bf16_f32 v177, v56, v57
	v_cvt_pk_bf16_f32 v178, v22, v23
	v_cvt_pk_bf16_f32 v179, v24, v25
	ds_bpermute_b32 v180, v151, v176
	ds_bpermute_b32 v181, v151, v177
	ds_bpermute_b32 v182, v151, v178
	ds_bpermute_b32 v183, v151, v179
	s_waitcnt lgkmcnt(4)
	global_store_dwordx4 v[140:141], v[164:167], off nt
	s_waitcnt lgkmcnt(0)
	global_store_dwordx4 v[140:141], v[180:183], off offset:256 nt
	s_branch .LBB0_126

.LBB0_150:
	s_andn2_b64 vcc, exec, s[76:77]
	s_cbranch_vccnz .LBB0_152
	v_lshl_add_u32 v135, v150, 4, v3
	v_and_b32_e32 v134, 15, v3
	v_sub_u32_e32 v134, v5, v134
	v_ashrrev_i32_e32 v136, 2, v135
	v_add_u32_e32 v134, v136, v134
	v_and_b32_e32 v137, 3, v3
	v_ashrrev_i32_e32 v136, 1, v135
	v_and_b32_e32 v136, -8, v136
	v_lshlrev_b32_e32 v138, 3, v137
	v_add_u32_e32 v138, v4, v138
	v_sub_u32_e32 v136, v138, v136
	v_lshlrev_b32_e32 v137, 6, v137
	v_and_or_b32 v151, v135, -4, v137
	v_readlane_b32 s0, v254, 43
	v_readlane_b32 s1, v254, 44
	v_ashrrev_i32_e32 v137, 31, v136
	v_ashrrev_i32_e32 v135, 31, v134
	v_lshlrev_b64 v[134:135], 9, v[134:135]
	v_lshl_add_u64 v[136:137], v[136:137], 1, s[0:1]
	v_lshl_add_u64 v[136:137], v[136:137], 0, v[134:135]
	s_branch .Lt_none9

.LBB0_153:
	s_and_b64 vcc, exec, s[76:77]
	s_cbranch_vccz .LBB0_155
	v_lshl_add_u32 v135, v150, 4, v3
	v_and_b32_e32 v134, 15, v3
	v_sub_u32_e32 v134, v5, v134
	v_ashrrev_i32_e32 v136, 2, v135
	v_add_u32_e32 v134, v136, v134
	v_and_b32_e32 v137, 3, v3
	v_ashrrev_i32_e32 v136, 1, v135
	v_and_b32_e32 v136, -8, v136
	v_lshlrev_b32_e32 v138, 3, v137
	s_lshl_b32 s0, s72, 8
	s_addk_i32 s0, 0xf000
	v_add3_u32 v138, s0, v4, v138
	v_sub_u32_e32 v136, v138, v136
	v_lshlrev_b32_e32 v137, 6, v137
	v_and_or_b32 v151, v135, -4, v137
	v_readlane_b32 s0, v254, 51
	v_readlane_b32 s1, v254, 52
	v_ashrrev_i32_e32 v137, 31, v136
	v_ashrrev_i32_e32 v135, 31, v134
	v_lshlrev_b64 v[134:135], 12, v[134:135]
	v_lshl_add_u64 v[136:137], v[136:137], 1, s[0:1]
	v_lshl_add_u64 v[136:137], v[136:137], 0, v[134:135]
	s_mov_b32 s84, 0x3e38aa3b
	s_mov_b32 s85, s84
	v_mov_b64_e32 v[138:139], v[136:137]
	v_pk_mul_f32 v[152:153], v[102:103], s[84:85] op_sel_hi:[1,0]
	v_pk_mul_f32 v[154:155], v[104:105], s[84:85] op_sel_hi:[1,0]
	v_pk_mul_f32 v[156:157], v[70:71], s[84:85] op_sel_hi:[1,0]
	v_pk_mul_f32 v[158:159], v[72:73], s[84:85] op_sel_hi:[1,0]
	v_cvt_pk_bf16_f32 v160, v152, v153
	v_cvt_pk_bf16_f32 v161, v154, v155
	v_cvt_pk_bf16_f32 v162, v156, v157
	v_cvt_pk_bf16_f32 v163, v158, v159
	ds_bpermute_b32 v164, v151, v160
	ds_bpermute_b32 v165, v151, v161
	ds_bpermute_b32 v166, v151, v162
	ds_bpermute_b32 v167, v151, v163
	v_pk_mul_f32 v[168:169], v[130:131], s[84:85] op_sel_hi:[1,0]
	v_pk_mul_f32 v[170:171], v[132:133], s[84:85] op_sel_hi:[1,0]
	v_pk_mul_f32 v[172:173], v[98:99], s[84:85] op_sel_hi:[1,0]
	v_pk_mul_f32 v[174:175], v[100:101], s[84:85] op_sel_hi:[1,0]
	v_cvt_pk_bf16_f32 v176, v168, v169
	v_cvt_pk_bf16_f32 v177, v170, v171
	v_cvt_pk_bf16_f32 v178, v172, v173
	v_cvt_pk_bf16_f32 v179, v174, v175
	ds_bpermute_b32 v180, v151, v176
	ds_bpermute_b32 v181, v151, v177
	ds_bpermute_b32 v182, v151, v178
	ds_bpermute_b32 v183, v151, v179
	s_waitcnt lgkmcnt(4)
	global_store_dwordx4 v[138:139], v[164:167], off nt
	s_mov_b64 s[2:3], 0x10000
	v_lshl_add_u64 v[140:141], v[136:137], 0, s[2:3]
	v_pk_mul_f32 v[152:153], v[114:115], s[84:85] op_sel_hi:[1,0]
	v_pk_mul_f32 v[154:155], v[116:117], s[84:85] op_sel_hi:[1,0]
	v_pk_mul_f32 v[156:157], v[82:83], s[84:85] op_sel_hi:[1,0]
	v_pk_mul_f32 v[158:159], v[84:85], s[84:85] op_sel_hi:[1,0]
	v_cvt_pk_bf16_f32 v160, v152, v153
	v_cvt_pk_bf16_f32 v161, v154, v155
	v_cvt_pk_bf16_f32 v162, v156, v157
	v_cvt_pk_bf16_f32 v163, v158, v159
	ds_bpermute_b32 v164, v151, v160
	ds_bpermute_b32 v165, v151, v161
	ds_bpermute_b32 v166, v151, v162
	ds_bpermute_b32 v167, v151, v163
	s_waitcnt lgkmcnt(4)
	global_store_dwordx4 v[138:139], v[180:183], off offset:256 nt
	v_pk_mul_f32 v[168:169], v[126:127], s[84:85] op_sel_hi:[1,0]
	v_pk_mul_f32 v[170:171], v[128:129], s[84:85] op_sel_hi:[1,0]
	v_pk_mul_f32 v[172:173], v[94:95], s[84:85] op_sel_hi:[1,0]
	v_pk_mul_f32 v[174:175], v[96:97], s[84:85] op_sel_hi:[1,0]
	v_cvt_pk_bf16_f32 v176, v168, v169
	v_cvt_pk_bf16_f32 v177, v170, v171
	v_cvt_pk_bf16_f32 v178, v172, v173
	v_cvt_pk_bf16_f32 v179, v174, v175
	ds_bpermute_b32 v180, v151, v176
	ds_bpermute_b32 v181, v151, v177
	ds_bpermute_b32 v182, v151, v178
	ds_bpermute_b32 v183, v151, v179
	s_waitcnt lgkmcnt(4)
	global_store_dwordx4 v[140:141], v[164:167], off nt
	s_mov_b64 s[2:3], 0x20000
	v_lshl_add_u64 v[138:139], v[136:137], 0, s[2:3]
	v_pk_mul_f32 v[152:153], v[110:111], s[84:85] op_sel_hi:[1,0]
	v_pk_mul_f32 v[154:155], v[112:113], s[84:85] op_sel_hi:[1,0]
	v_pk_mul_f32 v[156:157], v[78:79], s[84:85] op_sel_hi:[1,0]
	v_pk_mul_f32 v[158:159], v[80:81], s[84:85] op_sel_hi:[1,0]
	v_cvt_pk_bf16_f32 v160, v152, v153
	v_cvt_pk_bf16_f32 v161, v154, v155
	v_cvt_pk_bf16_f32 v162, v156, v157
	v_cvt_pk_bf16_f32 v163, v158, v159
	ds_bpermute_b32 v164, v151, v160
	ds_bpermute_b32 v165, v151, v161
	ds_bpermute_b32 v166, v151, v162
	ds_bpermute_b32 v167, v151, v163
	s_waitcnt lgkmcnt(4)
	global_store_dwordx4 v[140:141], v[180:183], off offset:256 nt
	v_pk_mul_f32 v[168:169], v[122:123], s[84:85] op_sel_hi:[1,0]
	v_pk_mul_f32 v[170:171], v[124:125], s[84:85] op_sel_hi:[1,0]
	v_pk_mul_f32 v[172:173], v[90:91], s[84:85] op_sel_hi:[1,0]
	v_pk_mul_f32 v[174:175], v[92:93], s[84:85] op_sel_hi:[1,0]
	v_cvt_pk_bf16_f32 v176, v168, v169
	v_cvt_pk_bf16_f32 v177, v170, v171
	v_cvt_pk_bf16_f32 v178, v172, v173
	v_cvt_pk_bf16_f32 v179, v174, v175
	ds_bpermute_b32 v180, v151, v176
	ds_bpermute_b32 v181, v151, v177
	ds_bpermute_b32 v182, v151, v178
	ds_bpermute_b32 v183, v151, v179
	s_waitcnt lgkmcnt(4)
	global_store_dwordx4 v[138:139], v[164:167], off nt
	s_mov_b64 s[2:3], 0x30000
	v_lshl_add_u64 v[140:141], v[136:137], 0, s[2:3]
	v_pk_mul_f32 v[152:153], v[106:107], s[84:85] op_sel_hi:[1,0]
	v_pk_mul_f32 v[154:155], v[108:109], s[84:85] op_sel_hi:[1,0]
	v_pk_mul_f32 v[156:157], v[74:75], s[84:85] op_sel_hi:[1,0]
	v_pk_mul_f32 v[158:159], v[76:77], s[84:85] op_sel_hi:[1,0]
	v_cvt_pk_bf16_f32 v160, v152, v153
	v_cvt_pk_bf16_f32 v161, v154, v155
	v_cvt_pk_bf16_f32 v162, v156, v157
	v_cvt_pk_bf16_f32 v163, v158, v159
	ds_bpermute_b32 v164, v151, v160
	ds_bpermute_b32 v165, v151, v161
	ds_bpermute_b32 v166, v151, v162
	ds_bpermute_b32 v167, v151, v163
	s_waitcnt lgkmcnt(4)
	global_store_dwordx4 v[138:139], v[180:183], off offset:256 nt
	v_pk_mul_f32 v[168:169], v[118:119], s[84:85] op_sel_hi:[1,0]
	v_pk_mul_f32 v[170:171], v[120:121], s[84:85] op_sel_hi:[1,0]
	v_pk_mul_f32 v[172:173], v[86:87], s[84:85] op_sel_hi:[1,0]
	v_pk_mul_f32 v[174:175], v[88:89], s[84:85] op_sel_hi:[1,0]
	v_cvt_pk_bf16_f32 v176, v168, v169
	v_cvt_pk_bf16_f32 v177, v170, v171
	v_cvt_pk_bf16_f32 v178, v172, v173
	v_cvt_pk_bf16_f32 v179, v174, v175
	ds_bpermute_b32 v180, v151, v176
	ds_bpermute_b32 v181, v151, v177
	ds_bpermute_b32 v182, v151, v178
	ds_bpermute_b32 v183, v151, v179
	s_waitcnt lgkmcnt(4)
	global_store_dwordx4 v[140:141], v[164:167], off nt
	s_mov_b64 s[2:3], 0x80000
	v_lshl_add_u64 v[138:139], v[136:137], 0, s[2:3]
	v_pk_mul_f32 v[152:153], v[38:39], s[84:85] op_sel_hi:[1,0]
	v_pk_mul_f32 v[154:155], v[40:41], s[84:85] op_sel_hi:[1,0]
	v_pk_mul_f32 v[156:157], v[6:7], s[84:85] op_sel_hi:[1,0]
	v_pk_mul_f32 v[158:159], v[8:9], s[84:85] op_sel_hi:[1,0]
	v_cvt_pk_bf16_f32 v160, v152, v153
	v_cvt_pk_bf16_f32 v161, v154, v155
	v_cvt_pk_bf16_f32 v162, v156, v157
	v_cvt_pk_bf16_f32 v163, v158, v159
	ds_bpermute_b32 v164, v151, v160
	ds_bpermute_b32 v165, v151, v161
	ds_bpermute_b32 v166, v151, v162
	ds_bpermute_b32 v167, v151, v163
	s_waitcnt lgkmcnt(4)
	global_store_dwordx4 v[140:141], v[180:183], off offset:256 nt
	v_pk_mul_f32 v[168:169], v[62:63], s[84:85] op_sel_hi:[1,0]
	v_pk_mul_f32 v[170:171], v[64:65], s[84:85] op_sel_hi:[1,0]
	v_pk_mul_f32 v[172:173], v[30:31], s[84:85] op_sel_hi:[1,0]
	v_pk_mul_f32 v[174:175], v[32:33], s[84:85] op_sel_hi:[1,0]
	v_cvt_pk_bf16_f32 v176, v168, v169
	v_cvt_pk_bf16_f32 v177, v170, v171
	v_cvt_pk_bf16_f32 v178, v172, v173
	v_cvt_pk_bf16_f32 v179, v174, v175
	ds_bpermute_b32 v180, v151, v176
	ds_bpermute_b32 v181, v151, v177
	ds_bpermute_b32 v182, v151, v178
	ds_bpermute_b32 v183, v151, v179
	s_waitcnt lgkmcnt(4)
	global_store_dwordx4 v[138:139], v[164:167], off nt
	s_mov_b64 s[2:3], 0x90000
	v_lshl_add_u64 v[140:141], v[136:137], 0, s[2:3]
	v_pk_mul_f32 v[152:153], v[50:51], s[84:85] op_sel_hi:[1,0]
	v_pk_mul_f32 v[154:155], v[52:53], s[84:85] op_sel_hi:[1,0]
	v_pk_mul_f32 v[156:157], v[18:19], s[84:85] op_sel_hi:[1,0]
	v_pk_mul_f32 v[158:159], v[20:21], s[84:85] op_sel_hi:[1,0]
	v_cvt_pk_bf16_f32 v160, v152, v153
	v_cvt_pk_bf16_f32 v161, v154, v155
	v_cvt_pk_bf16_f32 v162, v156, v157
	v_cvt_pk_bf16_f32 v163, v158, v159
	ds_bpermute_b32 v164, v151, v160
	ds_bpermute_b32 v165, v151, v161
	ds_bpermute_b32 v166, v151, v162
	ds_bpermute_b32 v167, v151, v163
	s_waitcnt lgkmcnt(4)
	global_store_dwordx4 v[138:139], v[180:183], off offset:256 nt
	v_pk_mul_f32 v[168:169], v[66:67], s[84:85] op_sel_hi:[1,0]
	v_pk_mul_f32 v[170:171], v[68:69], s[84:85] op_sel_hi:[1,0]
	v_pk_mul_f32 v[172:173], v[34:35], s[84:85] op_sel_hi:[1,0]
	v_pk_mul_f32 v[174:175], v[36:37], s[84:85] op_sel_hi:[1,0]
	v_cvt_pk_bf16_f32 v176, v168, v169
	v_cvt_pk_bf16_f32 v177, v170, v171
	v_cvt_pk_bf16_f32 v178, v172, v173
	v_cvt_pk_bf16_f32 v179, v174, v175
	ds_bpermute_b32 v180, v151, v176
	ds_bpermute_b32 v181, v151, v177
	ds_bpermute_b32 v182, v151, v178
	ds_bpermute_b32 v183, v151, v179
	s_waitcnt lgkmcnt(4)
	global_store_dwordx4 v[140:141], v[164:167], off nt
	s_mov_b64 s[2:3], 0xa0000
	v_lshl_add_u64 v[138:139], v[136:137], 0, s[2:3]
	v_pk_mul_f32 v[152:153], v[46:47], s[84:85] op_sel_hi:[1,0]
	v_pk_mul_f32 v[154:155], v[48:49], s[84:85] op_sel_hi:[1,0]
	v_pk_mul_f32 v[156:157], v[14:15], s[84:85] op_sel_hi:[1,0]
	v_pk_mul_f32 v[158:159], v[16:17], s[84:85] op_sel_hi:[1,0]
	v_cvt_pk_bf16_f32 v160, v152, v153
	v_cvt_pk_bf16_f32 v161, v154, v155
	v_cvt_pk_bf16_f32 v162, v156, v157
	v_cvt_pk_bf16_f32 v163, v158, v159
	ds_bpermute_b32 v164, v151, v160
	ds_bpermute_b32 v165, v151, v161
	ds_bpermute_b32 v166, v151, v162
	ds_bpermute_b32 v167, v151, v163
	s_waitcnt lgkmcnt(4)
	global_store_dwordx4 v[140:141], v[180:183], off offset:256 nt
	v_pk_mul_f32 v[168:169], v[58:59], s[84:85] op_sel_hi:[1,0]
	v_pk_mul_f32 v[170:171], v[60:61], s[84:85] op_sel_hi:[1,0]
	v_pk_mul_f32 v[172:173], v[26:27], s[84:85] op_sel_hi:[1,0]
	v_pk_mul_f32 v[174:175], v[28:29], s[84:85] op_sel_hi:[1,0]
	v_cvt_pk_bf16_f32 v176, v168, v169
	v_cvt_pk_bf16_f32 v177, v170, v171
	v_cvt_pk_bf16_f32 v178, v172, v173
	v_cvt_pk_bf16_f32 v179, v174, v175
	ds_bpermute_b32 v180, v151, v176
	ds_bpermute_b32 v181, v151, v177
	ds_bpermute_b32 v182, v151, v178
	ds_bpermute_b32 v183, v151, v179
	s_waitcnt lgkmcnt(4)
	global_store_dwordx4 v[138:139], v[164:167], off nt
	s_mov_b64 s[2:3], 0xb0000
	v_lshl_add_u64 v[140:141], v[136:137], 0, s[2:3]
	v_pk_mul_f32 v[152:153], v[42:43], s[84:85] op_sel_hi:[1,0]
	v_pk_mul_f32 v[154:155], v[44:45], s[84:85] op_sel_hi:[1,0]
	v_pk_mul_f32 v[156:157], v[10:11], s[84:85] op_sel_hi:[1,0]
	v_pk_mul_f32 v[158:159], v[12:13], s[84:85] op_sel_hi:[1,0]
	v_cvt_pk_bf16_f32 v160, v152, v153
	v_cvt_pk_bf16_f32 v161, v154, v155
	v_cvt_pk_bf16_f32 v162, v156, v157
	v_cvt_pk_bf16_f32 v163, v158, v159
	ds_bpermute_b32 v164, v151, v160
	ds_bpermute_b32 v165, v151, v161
	ds_bpermute_b32 v166, v151, v162
	ds_bpermute_b32 v167, v151, v163
	s_waitcnt lgkmcnt(4)
	global_store_dwordx4 v[138:139], v[180:183], off offset:256 nt
	v_pk_mul_f32 v[168:169], v[54:55], s[84:85] op_sel_hi:[1,0]
	v_pk_mul_f32 v[170:171], v[56:57], s[84:85] op_sel_hi:[1,0]
	v_pk_mul_f32 v[172:173], v[22:23], s[84:85] op_sel_hi:[1,0]
	v_pk_mul_f32 v[174:175], v[24:25], s[84:85] op_sel_hi:[1,0]
	v_cvt_pk_bf16_f32 v176, v168, v169
	v_cvt_pk_bf16_f32 v177, v170, v171
	v_cvt_pk_bf16_f32 v178, v172, v173
	v_cvt_pk_bf16_f32 v179, v174, v175
	ds_bpermute_b32 v180, v151, v176
	ds_bpermute_b32 v181, v151, v177
	ds_bpermute_b32 v182, v151, v178
	ds_bpermute_b32 v183, v151, v179
	s_waitcnt lgkmcnt(4)
	global_store_dwordx4 v[140:141], v[164:167], off nt
	s_waitcnt lgkmcnt(0)
	global_store_dwordx4 v[140:141], v[180:183], off offset:256 nt
	s_branch .LBB0_126

.LBB0_159:
	s_andn2_b64 vcc, exec, s[76:77]
	s_cbranch_vccnz .LBB0_161
	v_lshl_add_u32 v135, v150, 4, v3
	v_and_b32_e32 v134, 15, v3
	v_sub_u32_e32 v134, v5, v134
	v_ashrrev_i32_e32 v136, 2, v135
	v_add_u32_e32 v134, v136, v134
	v_and_b32_e32 v137, 3, v3
	v_ashrrev_i32_e32 v136, 1, v135
	v_and_b32_e32 v136, -8, v136
	v_lshlrev_b32_e32 v138, 3, v137
	s_lshl_b32 s0, s72, 8
	s_addk_i32 s0, 0xf800
	v_add3_u32 v138, s0, v4, v138
	v_sub_u32_e32 v136, v138, v136
	v_lshlrev_b32_e32 v137, 6, v137
	v_and_or_b32 v151, v135, -4, v137
	v_ashrrev_i32_e32 v137, 31, v136
	v_ashrrev_i32_e32 v135, 31, v134
	v_lshlrev_b64 v[134:135], 11, v[134:135]
	v_lshl_add_u64 v[136:137], v[136:137], 1, s[30:31]
	v_lshl_add_u64 v[136:137], v[136:137], 0, v[134:135]
	v_mov_b64_e32 v[138:139], v[136:137]
	v_cvt_pk_bf16_f32 v160, v102, v103
	v_cvt_pk_bf16_f32 v161, v104, v105
	v_cvt_pk_bf16_f32 v162, v70, v71
	v_cvt_pk_bf16_f32 v163, v72, v73
	ds_bpermute_b32 v164, v151, v160
	ds_bpermute_b32 v165, v151, v161
	ds_bpermute_b32 v166, v151, v162
	ds_bpermute_b32 v167, v151, v163
	v_cvt_pk_bf16_f32 v176, v130, v131
	v_cvt_pk_bf16_f32 v177, v132, v133
	v_cvt_pk_bf16_f32 v178, v98, v99
	v_cvt_pk_bf16_f32 v179, v100, v101
	ds_bpermute_b32 v180, v151, v176
	ds_bpermute_b32 v181, v151, v177
	ds_bpermute_b32 v182, v151, v178
	ds_bpermute_b32 v183, v151, v179
	s_waitcnt lgkmcnt(4)
	global_store_dwordx4 v[138:139], v[164:167], off nt
	s_mov_b64 s[2:3], 0x8000
	v_lshl_add_u64 v[140:141], v[136:137], 0, s[2:3]
	v_cvt_pk_bf16_f32 v160, v114, v115
	v_cvt_pk_bf16_f32 v161, v116, v117
	v_cvt_pk_bf16_f32 v162, v82, v83
	v_cvt_pk_bf16_f32 v163, v84, v85
	ds_bpermute_b32 v164, v151, v160
	ds_bpermute_b32 v165, v151, v161
	ds_bpermute_b32 v166, v151, v162
	ds_bpermute_b32 v167, v151, v163
	s_waitcnt lgkmcnt(4)
	global_store_dwordx4 v[138:139], v[180:183], off offset:256 nt
	v_cvt_pk_bf16_f32 v176, v126, v127
	v_cvt_pk_bf16_f32 v177, v128, v129
	v_cvt_pk_bf16_f32 v178, v94, v95
	v_cvt_pk_bf16_f32 v179, v96, v97
	ds_bpermute_b32 v180, v151, v176
	ds_bpermute_b32 v181, v151, v177
	ds_bpermute_b32 v182, v151, v178
	ds_bpermute_b32 v183, v151, v179
	s_waitcnt lgkmcnt(4)
	global_store_dwordx4 v[140:141], v[164:167], off nt
	s_mov_b64 s[2:3], 0x10000
	v_lshl_add_u64 v[138:139], v[136:137], 0, s[2:3]
	v_cvt_pk_bf16_f32 v160, v110, v111
	v_cvt_pk_bf16_f32 v161, v112, v113
	v_cvt_pk_bf16_f32 v162, v78, v79
	v_cvt_pk_bf16_f32 v163, v80, v81
	ds_bpermute_b32 v164, v151, v160
	ds_bpermute_b32 v165, v151, v161
	ds_bpermute_b32 v166, v151, v162
	ds_bpermute_b32 v167, v151, v163
	s_waitcnt lgkmcnt(4)
	global_store_dwordx4 v[140:141], v[180:183], off offset:256 nt
	v_cvt_pk_bf16_f32 v176, v122, v123
	v_cvt_pk_bf16_f32 v177, v124, v125
	v_cvt_pk_bf16_f32 v178, v90, v91
	v_cvt_pk_bf16_f32 v179, v92, v93
	ds_bpermute_b32 v180, v151, v176
	ds_bpermute_b32 v181, v151, v177
	ds_bpermute_b32 v182, v151, v178
	ds_bpermute_b32 v183, v151, v179
	s_waitcnt lgkmcnt(4)
	global_store_dwordx4 v[138:139], v[164:167], off nt
	s_mov_b64 s[2:3], 0x18000
	v_lshl_add_u64 v[140:141], v[136:137], 0, s[2:3]
	v_cvt_pk_bf16_f32 v160, v106, v107
	v_cvt_pk_bf16_f32 v161, v108, v109
	v_cvt_pk_bf16_f32 v162, v74, v75
	v_cvt_pk_bf16_f32 v163, v76, v77
	ds_bpermute_b32 v164, v151, v160
	ds_bpermute_b32 v165, v151, v161
	ds_bpermute_b32 v166, v151, v162
	ds_bpermute_b32 v167, v151, v163
	s_waitcnt lgkmcnt(4)
	global_store_dwordx4 v[138:139], v[180:183], off offset:256 nt
	v_cvt_pk_bf16_f32 v176, v118, v119
	v_cvt_pk_bf16_f32 v177, v120, v121
	v_cvt_pk_bf16_f32 v178, v86, v87
	v_cvt_pk_bf16_f32 v179, v88, v89
	ds_bpermute_b32 v180, v151, v176
	ds_bpermute_b32 v181, v151, v177
	ds_bpermute_b32 v182, v151, v178
	ds_bpermute_b32 v183, v151, v179
	s_waitcnt lgkmcnt(4)
	global_store_dwordx4 v[140:141], v[164:167], off nt
	s_mov_b64 s[2:3], 0x40000
	v_lshl_add_u64 v[138:139], v[136:137], 0, s[2:3]
	v_cvt_pk_bf16_f32 v160, v38, v39
	v_cvt_pk_bf16_f32 v161, v40, v41
	v_cvt_pk_bf16_f32 v162, v6, v7
	v_cvt_pk_bf16_f32 v163, v8, v9
	ds_bpermute_b32 v164, v151, v160
	ds_bpermute_b32 v165, v151, v161
	ds_bpermute_b32 v166, v151, v162
	ds_bpermute_b32 v167, v151, v163
	s_waitcnt lgkmcnt(4)
	global_store_dwordx4 v[140:141], v[180:183], off offset:256 nt
	v_cvt_pk_bf16_f32 v176, v62, v63
	v_cvt_pk_bf16_f32 v177, v64, v65
	v_cvt_pk_bf16_f32 v178, v30, v31
	v_cvt_pk_bf16_f32 v179, v32, v33
	ds_bpermute_b32 v180, v151, v176
	ds_bpermute_b32 v181, v151, v177
	ds_bpermute_b32 v182, v151, v178
	ds_bpermute_b32 v183, v151, v179
	s_waitcnt lgkmcnt(4)
	global_store_dwordx4 v[138:139], v[164:167], off nt
	s_mov_b64 s[2:3], 0x48000
	v_lshl_add_u64 v[140:141], v[136:137], 0, s[2:3]
	v_cvt_pk_bf16_f32 v160, v50, v51
	v_cvt_pk_bf16_f32 v161, v52, v53
	v_cvt_pk_bf16_f32 v162, v18, v19
	v_cvt_pk_bf16_f32 v163, v20, v21
	ds_bpermute_b32 v164, v151, v160
	ds_bpermute_b32 v165, v151, v161
	ds_bpermute_b32 v166, v151, v162
	ds_bpermute_b32 v167, v151, v163
	s_waitcnt lgkmcnt(4)
	global_store_dwordx4 v[138:139], v[180:183], off offset:256 nt
	v_cvt_pk_bf16_f32 v176, v66, v67
	v_cvt_pk_bf16_f32 v177, v68, v69
	v_cvt_pk_bf16_f32 v178, v34, v35
	v_cvt_pk_bf16_f32 v179, v36, v37
	ds_bpermute_b32 v180, v151, v176
	ds_bpermute_b32 v181, v151, v177
	ds_bpermute_b32 v182, v151, v178
	ds_bpermute_b32 v183, v151, v179
	s_waitcnt lgkmcnt(4)
	global_store_dwordx4 v[140:141], v[164:167], off nt
	s_mov_b64 s[2:3], 0x50000
	v_lshl_add_u64 v[138:139], v[136:137], 0, s[2:3]
	v_cvt_pk_bf16_f32 v160, v46, v47
	v_cvt_pk_bf16_f32 v161, v48, v49
	v_cvt_pk_bf16_f32 v162, v14, v15
	v_cvt_pk_bf16_f32 v163, v16, v17
	ds_bpermute_b32 v164, v151, v160
	ds_bpermute_b32 v165, v151, v161
	ds_bpermute_b32 v166, v151, v162
	ds_bpermute_b32 v167, v151, v163
	s_waitcnt lgkmcnt(4)
	global_store_dwordx4 v[140:141], v[180:183], off offset:256 nt
	v_cvt_pk_bf16_f32 v176, v58, v59
	v_cvt_pk_bf16_f32 v177, v60, v61
	v_cvt_pk_bf16_f32 v178, v26, v27
	v_cvt_pk_bf16_f32 v179, v28, v29
	ds_bpermute_b32 v180, v151, v176
	ds_bpermute_b32 v181, v151, v177
	ds_bpermute_b32 v182, v151, v178
	ds_bpermute_b32 v183, v151, v179
	s_waitcnt lgkmcnt(4)
	global_store_dwordx4 v[138:139], v[164:167], off nt
	s_mov_b64 s[2:3], 0x58000
	v_lshl_add_u64 v[140:141], v[136:137], 0, s[2:3]
	v_cvt_pk_bf16_f32 v160, v42, v43
	v_cvt_pk_bf16_f32 v161, v44, v45
	v_cvt_pk_bf16_f32 v162, v10, v11
	v_cvt_pk_bf16_f32 v163, v12, v13
	ds_bpermute_b32 v164, v151, v160
	ds_bpermute_b32 v165, v151, v161
	ds_bpermute_b32 v166, v151, v162
	ds_bpermute_b32 v167, v151, v163
	s_waitcnt lgkmcnt(4)
	global_store_dwordx4 v[138:139], v[180:183], off offset:256 nt
	v_cvt_pk_bf16_f32 v176, v54, v55
	v_cvt_pk_bf16_f32 v177, v56, v57
	v_cvt_pk_bf16_f32 v178, v22, v23
	v_cvt_pk_bf16_f32 v179, v24, v25
	ds_bpermute_b32 v180, v151, v176
	ds_bpermute_b32 v181, v151, v177
	ds_bpermute_b32 v182, v151, v178
	ds_bpermute_b32 v183, v151, v179
	s_waitcnt lgkmcnt(4)
	global_store_dwordx4 v[140:141], v[164:167], off nt
	s_waitcnt lgkmcnt(0)
	global_store_dwordx4 v[140:141], v[180:183], off offset:256 nt
	s_branch .LBB0_126
